# fastdiv version + nt (streaming) hint on the once-read f32 weight loads of the transposes
# speedup vs baseline: 1.0041x; 1.0041x over previous
; #define LAS __attribute__((address_space(3)))
; template <int MODE> DI void transpose_job(LAS unsigned char* lds, const float* src, int K, int N, bf16_t* dst, int bid, int nblk) {
;     ...
;     for (int t0 = bid; t0 < ntile; t0 += 2 * nblk) {
; #pragma unroll
;         for (int q = 0; q < 2; ++q) { const int t = t0 + q * nblk; LAS float* tl = (LAS float*)(lds + q * 16640);
;             if (t < ntile) { const int k0 = (t / tn) * 64, n0 = (t % tn) * 64;
; #pragma unroll
;                 for (int i = 0; i < 2; ++i) { const int kk = (tid >> 4) + 32 * i, nn = (tid & 15) * 4;
;                     f32x4 v = {0.f, 0.f, 0.f, 0.f}; if (n0 + nn < N) v = *(const f32x4*)(src + (size_t)(k0 + kk) * N + n0 + nn);
;                     tl[kk * 65 + nn] = v[0]; tl[kk * 65 + nn + 1] = v[1]; tl[kk * 65 + nn + 2] = v[2]; tl[kk * 65 + nn + 3] = v[3]; } } }
; DI void phase_weights_b(LAS unsigned char* lds, PP p, int l, int bid, int nblk) {
;     ...
;     transpose_job<0>(lds, p->in[20] + (size_t)l * 1024 * 2048, 1024, 2048, (bf16_t*)(ws + O_WUPG), bid, nblk);
.LBB0_168:
	s_ashr_i32 s20, s30, 31
	s_lshr_b32 s20, s20, 27
	s_add_i32 s31, s30, s20
	s_and_b32 s20, s31, 0x3ffffe0
	s_sub_i32 s20, s30, s20
	s_lshl_b32 s20, s20, 6
	v_or_b32_e32 v2, s20, v14
	s_movk_i32 s21, 0x800
	v_cmp_gt_i32_e32 vcc, s21, v2
	v_mov_b32_e32 v4, 0
	v_mov_b32_e32 v5, 0
	v_mov_b32_e32 v6, 0
	v_mov_b32_e32 v7, 0
	v_mov_b32_e32 v8, 0
	v_mov_b32_e32 v9, 0
	v_mov_b32_e32 v10, 0
	v_mov_b32_e32 v11, 0
	s_and_saveexec_b64 s[22:23], vcc
	s_cbranch_execz .LBB0_170
	s_ashr_i32 s21, s20, 31
	v_lshl_add_u64 v[4:5], s[20:21], 2, v[0:1]
	s_lshl_b32 s21, s31, 1
	s_andn2_b32 s21, s21, 63
	v_add_u32_e32 v6, s21, v13
	v_add_u32_e32 v8, s21, v17
	v_ashrrev_i32_e32 v7, 31, v6
	v_ashrrev_i32_e32 v9, 31, v8
	v_lshlrev_b64 v[6:7], 13, v[6:7]
	v_lshlrev_b64 v[8:9], 13, v[8:9]
	v_lshl_add_u64 v[6:7], v[4:5], 0, v[6:7]
	v_lshl_add_u64 v[4:5], v[4:5], 0, v[8:9]
	global_load_dwordx4 v[8:11], v[6:7], off nt
	s_nop 0
	global_load_dwordx4 v[4:7], v[4:5], off nt
.LBB0_170:
	s_or_b64 exec, exec, s[22:23]
	s_add_i32 s21, s85, s30
	s_sub_i32 s34, s21, 32
	v_add_u32_e32 v2, 0x2080, v19
	s_cmpk_lt_i32 s34, 0x200
	s_waitcnt vmcnt(1)
	ds_write2_b32 v19, v8, v9 offset1:1
	ds_write2_b32 v19, v10, v11 offset0:2 offset1:3
	s_waitcnt vmcnt(0)
	ds_write2_b32 v2, v4, v5 offset1:1
	v_add_u32_e32 v2, 0x2088, v19
	s_cselect_b64 s[22:23], -1, 0
	s_cmpk_gt_i32 s34, 0x1ff
	ds_write2_b32 v2, v6, v7 offset1:1
	s_cbranch_scc1 .LBB0_174
	s_ashr_i32 s21, s34, 31
	s_lshr_b32 s21, s21, 27
	s_add_i32 s21, s34, s21
	s_and_b32 s26, s21, 0x3ffffe0
	s_sub_i32 s26, s34, s26
	s_lshl_b32 s28, s26, 6
	v_or_b32_e32 v2, s28, v14
	s_movk_i32 s26, 0x800
	v_cmp_gt_i32_e32 vcc, s26, v2
	v_mov_b32_e32 v4, 0
	v_mov_b32_e32 v5, 0
	v_mov_b32_e32 v6, 0
	v_mov_b32_e32 v7, 0
	v_mov_b32_e32 v8, 0
	v_mov_b32_e32 v9, 0
	v_mov_b32_e32 v10, 0
	v_mov_b32_e32 v11, 0
	s_and_saveexec_b64 s[26:27], vcc
	s_cbranch_execz .LBB0_173
	s_lshl_b32 s21, s21, 1
	s_andn2_b32 s21, s21, 63
	v_add_u32_e32 v6, s21, v13
	v_add_u32_e32 v8, s21, v17
	s_ashr_i32 s29, s28, 31
	v_ashrrev_i32_e32 v7, 31, v6
	v_ashrrev_i32_e32 v9, 31, v8
	v_lshl_add_u64 v[4:5], s[28:29], 2, v[0:1]
	v_lshlrev_b64 v[6:7], 13, v[6:7]
	v_lshlrev_b64 v[8:9], 13, v[8:9]
	v_lshl_add_u64 v[6:7], v[4:5], 0, v[6:7]
	v_lshl_add_u64 v[4:5], v[4:5], 0, v[8:9]
	global_load_dwordx4 v[8:11], v[6:7], off nt
	s_nop 0
	global_load_dwordx4 v[4:7], v[4:5], off nt

; #define LAS __attribute__((address_space(3)))
; template <int MODE> DI void transpose_job(LAS unsigned char* lds, const float* src, int K, int N, bf16_t* dst, int bid, int nblk) {
;     ...
;     for (int t0 = bid; t0 < ntile; t0 += 2 * nblk) {
; #pragma unroll
;         for (int q = 0; q < 2; ++q) { const int t = t0 + q * nblk; LAS float* tl = (LAS float*)(lds + q * 16640);
;             if (t < ntile) { const int k0 = (t / tn) * 64, n0 = (t % tn) * 64;
; #pragma unroll
;                 for (int i = 0; i < 2; ++i) { const int kk = (tid >> 4) + 32 * i, nn = (tid & 15) * 4;
;                     f32x4 v = {0.f, 0.f, 0.f, 0.f}; if (n0 + nn < N) v = *(const f32x4*)(src + (size_t)(k0 + kk) * N + n0 + nn);
;                     tl[kk * 65 + nn] = v[0]; tl[kk * 65 + nn + 1] = v[1]; tl[kk * 65 + nn + 2] = v[2]; tl[kk * 65 + nn + 3] = v[3]; } } }
; DI void phase_weights_b(LAS unsigned char* lds, PP p, int l, int bid, int nblk) {
;     ...
;     transpose_job<0>(lds, p->in[21] + (size_t)l * 2048 * 2048, 2048, 2048, (bf16_t*)(ws + O_WOUT), bid, nblk);
.LBB0_185:
	s_or_b64 exec, exec, s[22:23]
	s_add_i32 s21, s85, s30
	s_sub_i32 s34, s21, 32
	v_add_u32_e32 v2, 0x2080, v19
	s_cmpk_lt_i32 s34, 0x400
	s_waitcnt vmcnt(1)
	ds_write2_b32 v19, v8, v9 offset1:1
	ds_write2_b32 v19, v10, v11 offset0:2 offset1:3
	s_waitcnt vmcnt(0)
	ds_write2_b32 v2, v4, v5 offset1:1
	v_add_u32_e32 v2, 0x2088, v19
	s_cselect_b64 s[22:23], -1, 0
	s_cmpk_gt_i32 s34, 0x3ff
	ds_write2_b32 v2, v6, v7 offset1:1
	s_cbranch_scc1 .LBB0_189
	s_ashr_i32 s21, s34, 31
	s_lshr_b32 s21, s21, 27
	s_add_i32 s21, s34, s21
	s_and_b32 s26, s21, 0x3ffffe0
	s_sub_i32 s26, s34, s26
	s_lshl_b32 s28, s26, 6
	v_or_b32_e32 v2, s28, v14
	s_movk_i32 s26, 0x800
	v_cmp_gt_i32_e32 vcc, s26, v2
	v_mov_b32_e32 v4, 0
	v_mov_b32_e32 v5, 0
	v_mov_b32_e32 v6, 0
	v_mov_b32_e32 v7, 0
	v_mov_b32_e32 v8, 0
	v_mov_b32_e32 v9, 0
	v_mov_b32_e32 v10, 0
	v_mov_b32_e32 v11, 0
	s_and_saveexec_b64 s[26:27], vcc
	s_cbranch_execz .LBB0_188
	s_lshl_b32 s21, s21, 1
	s_andn2_b32 s21, s21, 63
	v_add_u32_e32 v6, s21, v13
	v_add_u32_e32 v8, s21, v17
	s_ashr_i32 s29, s28, 31
	v_ashrrev_i32_e32 v7, 31, v6
	v_ashrrev_i32_e32 v9, 31, v8
	v_lshl_add_u64 v[4:5], s[28:29], 2, v[0:1]
	v_lshlrev_b64 v[6:7], 13, v[6:7]
	v_lshlrev_b64 v[8:9], 13, v[8:9]
	v_lshl_add_u64 v[6:7], v[4:5], 0, v[6:7]
	v_lshl_add_u64 v[4:5], v[4:5], 0, v[8:9]
	global_load_dwordx4 v[8:11], v[6:7], off nt
	s_nop 0
	global_load_dwordx4 v[4:7], v[4:5], off nt

; #define LAS __attribute__((address_space(3)))
; template <int MODE> DI void transpose_job(LAS unsigned char* lds, const float* src, int K, int N, bf16_t* dst, int bid, int nblk) {
;     ...
;     for (int t0 = bid; t0 < ntile; t0 += 2 * nblk) {
; #pragma unroll
;         for (int q = 0; q < 2; ++q) { const int t = t0 + q * nblk; LAS float* tl = (LAS float*)(lds + q * 16640);
;             if (t < ntile) { const int k0 = (t / tn) * 64, n0 = (t % tn) * 64;
; #pragma unroll
;                 for (int i = 0; i < 2; ++i) { const int kk = (tid >> 4) + 32 * i, nn = (tid & 15) * 4;
;                     f32x4 v = {0.f, 0.f, 0.f, 0.f}; if (n0 + nn < N) v = *(const f32x4*)(src + (size_t)(k0 + kk) * N + n0 + nn);
;                     tl[kk * 65 + nn] = v[0]; tl[kk * 65 + nn + 1] = v[1]; tl[kk * 65 + nn + 2] = v[2]; tl[kk * 65 + nn + 3] = v[3]; } } }
; DI void phase_weights_b(LAS unsigned char* lds, PP p, int l, int bid, int nblk) {
;     ...
;     transpose_job<2>(lds, p->in[24] + (size_t)l * 2048 * 11264, 2048, 11264, (bf16_t*)(ws + O_WF1), bid, nblk);
.LBB0_199:
	s_mul_hi_i32 s20, s30, 0x2e8ba2e9
	s_lshr_b32 s21, s20, 31
	s_ashr_i32 s20, s20, 5
	s_add_i32 s21, s20, s21
	s_lshl_b32 s20, s21, 6
	s_mulk_i32 s21, 0xb0
	s_sub_i32 s21, s30, s21
	s_lshl_b32 s26, s21, 6
	s_ashr_i32 s27, s26, 31
	v_lshl_add_u64 v[10:11], s[26:27], 2, v[0:1]
	v_add_u32_e32 v2, s20, v5
	s_mov_b32 s21, 0xb000
	v_mad_i64_i32 v[6:7], s[22:23], v2, s21, v[10:11]
	global_load_dwordx4 v[6:9], v[6:7], off nt
	v_add_u32_e32 v2, s20, v18
	s_waitcnt vmcnt(0)
	ds_write2_b32 v20, v6, v7 offset1:1
	ds_write2_b32 v20, v8, v9 offset0:2 offset1:3
	v_mad_i64_i32 v[6:7], s[22:23], v2, s21, v[10:11]
	global_load_dwordx4 v[6:9], v[6:7], off nt
	s_add_i32 s21, s85, s30
	s_sub_i32 s31, s21, 32
	v_add_u32_e32 v2, 0x2080, v20
	s_cmpk_lt_i32 s31, 0x1600
	s_cselect_b64 s[22:23], -1, 0
	s_cmpk_gt_i32 s31, 0x15ff
	s_mul_hi_i32 s34, s31, 0x2e8ba2e9
	s_waitcnt vmcnt(0)
	ds_write2_b32 v2, v6, v7 offset1:1
	v_add_u32_e32 v2, 0x2088, v20
	ds_write2_b32 v2, v8, v9 offset1:1
	s_cbranch_scc1 .LBB0_201
	s_lshr_b32 s21, s34, 31
	s_ashr_i32 s27, s34, 5
	s_add_i32 s21, s27, s21
	s_lshl_b32 s27, s21, 6
	s_mulk_i32 s21, 0xb0
	s_sub_i32 s21, s31, s21
	s_lshl_b32 s28, s21, 6
	s_ashr_i32 s29, s28, 31
	v_lshl_add_u64 v[10:11], s[28:29], 2, v[0:1]
	v_add_u32_e32 v2, s27, v5
	s_mov_b32 s21, 0xb000
	v_mad_i64_i32 v[6:7], s[28:29], v2, s21, v[10:11]
	global_load_dwordx4 v[6:9], v[6:7], off nt
	v_add_u32_e32 v2, 0x4100, v20
	s_waitcnt vmcnt(0)
	ds_write2_b32 v2, v6, v7 offset1:1
	v_add_u32_e32 v2, 0x4108, v20
	ds_write2_b32 v2, v8, v9 offset1:1
	v_add_u32_e32 v2, s27, v18
	v_mad_i64_i32 v[6:7], s[28:29], v2, s21, v[10:11]
	global_load_dwordx4 v[6:9], v[6:7], off nt
	v_add_u32_e32 v2, 0x6180, v20
	s_waitcnt vmcnt(0)
	ds_write2_b32 v2, v6, v7 offset1:1
	v_add_u32_e32 v2, 0x6188, v20
	ds_write2_b32 v2, v8, v9 offset1:1

; #define LAS __attribute__((address_space(3)))
; template <int MODE> DI void transpose_job(LAS unsigned char* lds, const float* src, int K, int N, bf16_t* dst, int bid, int nblk) {
;     ...
;     for (int t0 = bid; t0 < ntile; t0 += 2 * nblk) {
; #pragma unroll
;         for (int q = 0; q < 2; ++q) { const int t = t0 + q * nblk; LAS float* tl = (LAS float*)(lds + q * 16640);
;             if (t < ntile) { const int k0 = (t / tn) * 64, n0 = (t % tn) * 64;
; #pragma unroll
;                 for (int i = 0; i < 2; ++i) { const int kk = (tid >> 4) + 32 * i, nn = (tid & 15) * 4;
;                     f32x4 v = {0.f, 0.f, 0.f, 0.f}; if (n0 + nn < N) v = *(const f32x4*)(src + (size_t)(k0 + kk) * N + n0 + nn);
;                     tl[kk * 65 + nn] = v[0]; tl[kk * 65 + nn + 1] = v[1]; tl[kk * 65 + nn + 2] = v[2]; tl[kk * 65 + nn + 3] = v[3]; } } }
; DI void phase_weights_b(LAS unsigned char* lds, PP p, int l, int bid, int nblk) {
;     ...
;     transpose_job<0>(lds, p->in[25] + (size_t)l * 5632 * 2048, 5632, 2048, (bf16_t*)(ws + O_WF2), bid, nblk);
.LBB0_219:
	s_or_b64 exec, exec, s[22:23]
	s_add_i32 s21, s85, s30
	s_sub_i32 s34, s21, 32
	v_add_u32_e32 v2, 0x2080, v19
	s_cmpk_lt_i32 s34, 0xb00
	s_waitcnt vmcnt(1)
	ds_write2_b32 v19, v8, v9 offset1:1
	ds_write2_b32 v19, v10, v11 offset0:2 offset1:3
	s_waitcnt vmcnt(0)
	ds_write2_b32 v2, v4, v5 offset1:1
	v_add_u32_e32 v2, 0x2088, v19
	s_cselect_b64 s[22:23], -1, 0
	s_cmpk_gt_i32 s34, 0xaff
	ds_write2_b32 v2, v6, v7 offset1:1
	s_cbranch_scc1 .LBB0_223
	s_ashr_i32 s21, s34, 31
	s_lshr_b32 s21, s21, 27
	s_add_i32 s21, s34, s21
	s_and_b32 s26, s21, 0x3ffffe0
	s_sub_i32 s26, s34, s26
	s_lshl_b32 s28, s26, 6
	v_or_b32_e32 v2, s28, v14
	s_movk_i32 s26, 0x800
	v_cmp_gt_i32_e32 vcc, s26, v2
	v_mov_b32_e32 v4, 0
	v_mov_b32_e32 v5, 0
	v_mov_b32_e32 v6, 0
	v_mov_b32_e32 v7, 0
	v_mov_b32_e32 v8, 0
	v_mov_b32_e32 v9, 0
	v_mov_b32_e32 v10, 0
	v_mov_b32_e32 v11, 0
	s_and_saveexec_b64 s[26:27], vcc
	s_cbranch_execz .LBB0_222
	s_lshl_b32 s21, s21, 1
	s_andn2_b32 s21, s21, 63
	v_add_u32_e32 v6, s21, v13
	v_add_u32_e32 v8, s21, v17
	s_ashr_i32 s29, s28, 31
	v_ashrrev_i32_e32 v7, 31, v6
	v_ashrrev_i32_e32 v9, 31, v8
	v_lshl_add_u64 v[4:5], s[28:29], 2, v[0:1]
	v_lshlrev_b64 v[6:7], 13, v[6:7]
	v_lshlrev_b64 v[8:9], 13, v[8:9]
	v_lshl_add_u64 v[6:7], v[4:5], 0, v[6:7]
	v_lshl_add_u64 v[4:5], v[4:5], 0, v[8:9]
	global_load_dwordx4 v[8:11], v[6:7], off nt
	s_nop 0
	global_load_dwordx4 v[4:7], v[4:5], off nt

; #define LAS __attribute__((address_space(3)))
; template <int MODE> DI void transpose_job(LAS unsigned char* lds, const float* src, int K, int N, bf16_t* dst, int bid, int nblk) {
;     ...
;     for (int t0 = bid; t0 < ntile; t0 += 2 * nblk) {
; #pragma unroll
;         for (int q = 0; q < 2; ++q) { const int t = t0 + q * nblk; LAS float* tl = (LAS float*)(lds + q * 16640);
;             if (t < ntile) { const int k0 = (t / tn) * 64, n0 = (t % tn) * 64;
; #pragma unroll
;                 for (int i = 0; i < 2; ++i) { const int kk = (tid >> 4) + 32 * i, nn = (tid & 15) * 4;
;                     f32x4 v = {0.f, 0.f, 0.f, 0.f}; if (n0 + nn < N) v = *(const f32x4*)(src + (size_t)(k0 + kk) * N + n0 + nn);
;                     tl[kk * 65 + nn] = v[0]; tl[kk * 65 + nn + 1] = v[1]; tl[kk * 65 + nn + 2] = v[2]; tl[kk * 65 + nn + 3] = v[3]; } } }
; DI void phase_weights_a(LAS unsigned char* lds, PP p, int l, int bid, int nblk) {
;     ...
;     transpose_job<1>(lds, p->in[4] + (size_t)l * 2048 * 9232, 2048, 9232, (bf16_t*)(ws + O_WIN), bid, nblk);
.LBB0_296:
	s_mul_hi_i32 s2, s26, 0xe1fc780f
	s_add_i32 s2, s2, s26
	s_lshr_b32 s3, s2, 31
	s_ashr_i32 s27, s2, 7
	s_add_i32 s27, s27, s3
	s_mul_i32 s2, s27, 0x91
	s_sub_i32 s2, s26, s2
	s_lshl_b32 s20, s2, 6
	v_or_b32_e32 v2, s20, v16
	s_movk_i32 s2, 0x2410
	v_cmp_gt_i32_e32 vcc, s2, v2
	v_mov_b32_e32 v4, 0
	v_mov_b32_e32 v5, 0
	v_mov_b32_e32 v6, 0
	v_mov_b32_e32 v7, 0
	v_mov_b32_e32 v8, 0
	v_mov_b32_e32 v9, 0
	v_mov_b32_e32 v10, 0
	v_mov_b32_e32 v11, 0
	s_and_saveexec_b64 s[2:3], vcc
	s_cbranch_execz .LBB0_298
	s_ashr_i32 s21, s20, 31
	v_lshl_add_u64 v[4:5], s[20:21], 2, v[0:1]
	s_lshl_b32 s21, s27, 6
	v_add_u32_e32 v2, s21, v13
	s_mov_b32 s24, 0x9040
	v_mad_i64_i32 v[6:7], s[22:23], v2, s24, v[4:5]
	v_add_u32_e32 v2, s21, v19
	v_mad_i64_i32 v[4:5], s[22:23], v2, s24, v[4:5]
	global_load_dwordx4 v[8:11], v[6:7], off nt
	s_nop 0
	global_load_dwordx4 v[4:7], v[4:5], off nt
.LBB0_298:
	s_or_b64 exec, exec, s[2:3]
	s_add_i32 s28, s85, s26
	s_addk_i32 s28, 0xffa0
	v_add_u32_e32 v2, 0x2080, v21
	s_cmpk_lt_i32 s28, 0x1220
	s_waitcnt vmcnt(1)
	ds_write2_b32 v21, v8, v9 offset1:1
	ds_write2_b32 v21, v10, v11 offset0:2 offset1:3
	s_waitcnt vmcnt(0)
	ds_write2_b32 v2, v4, v5 offset1:1
	v_add_u32_e32 v2, 0x2088, v21
	s_cselect_b64 s[2:3], -1, 0
	s_cmpk_gt_i32 s28, 0x121f
	s_mul_hi_i32 s29, s28, 0xe1fc780f
	ds_write2_b32 v2, v6, v7 offset1:1
	s_cbranch_scc1 .LBB0_302
	s_add_i32 s21, s29, s28
	s_lshr_b32 s22, s21, 31
	s_ashr_i32 s21, s21, 7
	s_add_i32 s21, s21, s22
	s_mul_i32 s22, s21, 0x91
	s_sub_i32 s22, s28, s22
	s_lshl_b32 s24, s22, 6
	v_or_b32_e32 v2, s24, v16
	s_movk_i32 s22, 0x2410
	v_cmp_gt_i32_e32 vcc, s22, v2
	v_mov_b32_e32 v4, 0
	v_mov_b32_e32 v5, 0
	v_mov_b32_e32 v6, 0
	v_mov_b32_e32 v7, 0
	v_mov_b32_e32 v8, 0
	v_mov_b32_e32 v9, 0
	v_mov_b32_e32 v10, 0
	v_mov_b32_e32 v11, 0
	s_and_saveexec_b64 s[22:23], vcc
	s_cbranch_execz .LBB0_301
	s_ashr_i32 s25, s24, 31
	s_lshl_b32 s21, s21, 6
	v_lshl_add_u64 v[4:5], s[24:25], 2, v[0:1]
	v_add_u32_e32 v2, s21, v13
	s_mov_b32 s30, 0x9040
	v_mad_i64_i32 v[6:7], s[24:25], v2, s30, v[4:5]
	v_add_u32_e32 v2, s21, v19
	v_mad_i64_i32 v[4:5], s[24:25], v2, s30, v[4:5]
	global_load_dwordx4 v[8:11], v[6:7], off nt
	s_nop 0
	global_load_dwordx4 v[4:7], v[4:5], off nt

; #define LAS __attribute__((address_space(3)))
; template <int MODE> DI void transpose_job(LAS unsigned char* lds, const float* src, int K, int N, bf16_t* dst, int bid, int nblk) {
;     ...
;     for (int t0 = bid; t0 < ntile; t0 += 2 * nblk) {
; #pragma unroll
;         for (int q = 0; q < 2; ++q) { const int t = t0 + q * nblk; LAS float* tl = (LAS float*)(lds + q * 16640);
;             if (t < ntile) { const int k0 = (t / tn) * 64, n0 = (t % tn) * 64;
; #pragma unroll
;                 for (int i = 0; i < 2; ++i) { const int kk = (tid >> 4) + 32 * i, nn = (tid & 15) * 4;
;                     f32x4 v = {0.f, 0.f, 0.f, 0.f}; if (n0 + nn < N) v = *(const f32x4*)(src + (size_t)(k0 + kk) * N + n0 + nn);
;                     tl[kk * 65 + nn] = v[0]; tl[kk * 65 + nn + 1] = v[1]; tl[kk * 65 + nn + 2] = v[2]; tl[kk * 65 + nn + 3] = v[3]; } } }
; DI void phase_weights_a(LAS unsigned char* lds, PP p, int l, int bid, int nblk) {
;     ...
;     transpose_job<0>(lds, p->in[13] + (size_t)l * 1024 * 1024, 1024, 1024, (bf16_t*)(ws + O_WGLU), bid, nblk);
.LBB0_321:
	s_ashr_i32 s2, s26, 31
	s_lshr_b32 s2, s2, 28
	s_add_i32 s27, s26, s2
	s_and_b32 s2, s27, 0x3fffff0
	s_sub_i32 s2, s26, s2
	s_lshl_b32 s2, s2, 6
	v_or_b32_e32 v2, s2, v14
	s_movk_i32 s3, 0x400
	v_cmp_gt_i32_e32 vcc, s3, v2
	v_mov_b32_e32 v4, 0
	v_mov_b32_e32 v5, 0
	v_mov_b32_e32 v6, 0
	v_mov_b32_e32 v7, 0
	v_mov_b32_e32 v8, 0
	v_mov_b32_e32 v9, 0
	v_mov_b32_e32 v10, 0
	v_mov_b32_e32 v11, 0
	s_and_saveexec_b64 s[20:21], vcc
	s_cbranch_execz .LBB0_323
	s_ashr_i32 s3, s2, 31
	v_lshl_add_u64 v[4:5], s[2:3], 2, v[0:1]
	s_lshl_b32 s3, s27, 2
	s_andn2_b32 s3, s3, 63
	v_add_u32_e32 v6, s3, v13
	v_add_u32_e32 v8, s3, v17
	v_ashrrev_i32_e32 v7, 31, v6
	v_ashrrev_i32_e32 v9, 31, v8
	v_lshlrev_b64 v[6:7], 12, v[6:7]
	v_lshlrev_b64 v[8:9], 12, v[8:9]
	v_lshl_add_u64 v[6:7], v[4:5], 0, v[6:7]
	v_lshl_add_u64 v[4:5], v[4:5], 0, v[8:9]
	global_load_dwordx4 v[8:11], v[6:7], off nt
	s_nop 0
	global_load_dwordx4 v[4:7], v[4:5], off nt
.LBB0_323:
	s_or_b64 exec, exec, s[20:21]
	s_add_i32 s28, s85, s26
	s_addk_i32 s28, 0xffa0
	v_add_u32_e32 v2, 0x2080, v19
	s_cmpk_lt_i32 s28, 0x100
	s_waitcnt vmcnt(1)
	ds_write2_b32 v19, v8, v9 offset1:1
	ds_write2_b32 v19, v10, v11 offset0:2 offset1:3
	s_waitcnt vmcnt(0)
	ds_write2_b32 v2, v4, v5 offset1:1
	v_add_u32_e32 v2, 0x2088, v19
	s_cselect_b64 s[20:21], -1, 0
	s_cmpk_gt_i32 s28, 0xff
	ds_write2_b32 v2, v6, v7 offset1:1
	s_cbranch_scc1 .LBB0_327
	s_ashr_i32 s3, s28, 31
	s_lshr_b32 s3, s3, 28
	s_add_i32 s3, s28, s3
	s_and_b32 s22, s3, 0x3fffff0
	s_sub_i32 s22, s28, s22
	s_lshl_b32 s24, s22, 6
	v_or_b32_e32 v2, s24, v14
	s_movk_i32 s22, 0x400
	v_cmp_gt_i32_e32 vcc, s22, v2
	v_mov_b32_e32 v4, 0
	v_mov_b32_e32 v5, 0
	v_mov_b32_e32 v6, 0
	v_mov_b32_e32 v7, 0
	v_mov_b32_e32 v8, 0
	v_mov_b32_e32 v9, 0
	v_mov_b32_e32 v10, 0
	v_mov_b32_e32 v11, 0
	s_and_saveexec_b64 s[22:23], vcc
	s_cbranch_execz .LBB0_326
	s_lshl_b32 s3, s3, 2
	s_andn2_b32 s3, s3, 63
	v_add_u32_e32 v6, s3, v13
	v_add_u32_e32 v8, s3, v17
	s_ashr_i32 s25, s24, 31
	v_ashrrev_i32_e32 v7, 31, v6
	v_ashrrev_i32_e32 v9, 31, v8
	v_lshl_add_u64 v[4:5], s[24:25], 2, v[0:1]
	v_lshlrev_b64 v[6:7], 12, v[6:7]
	v_lshlrev_b64 v[8:9], 12, v[8:9]
	v_lshl_add_u64 v[6:7], v[4:5], 0, v[6:7]
	v_lshl_add_u64 v[4:5], v[4:5], 0, v[8:9]
	global_load_dwordx4 v[8:11], v[6:7], off nt
	s_nop 0
	global_load_dwordx4 v[4:7], v[4:5], off nt

; #define LAS __attribute__((address_space(3)))
; template <int MODE> DI void transpose_job(LAS unsigned char* lds, const float* src, int K, int N, bf16_t* dst, int bid, int nblk) {
;     ...
;     for (int t0 = bid; t0 < ntile; t0 += 2 * nblk) {
; #pragma unroll
;         for (int q = 0; q < 2; ++q) { const int t = t0 + q * nblk; LAS float* tl = (LAS float*)(lds + q * 16640);
;             if (t < ntile) { const int k0 = (t / tn) * 64, n0 = (t % tn) * 64;
; #pragma unroll
;                 for (int i = 0; i < 2; ++i) { const int kk = (tid >> 4) + 32 * i, nn = (tid & 15) * 4;
;                     f32x4 v = {0.f, 0.f, 0.f, 0.f}; if (n0 + nn < N) v = *(const f32x4*)(src + (size_t)(k0 + kk) * N + n0 + nn);
;                     tl[kk * 65 + nn] = v[0]; tl[kk * 65 + nn + 1] = v[1]; tl[kk * 65 + nn + 2] = v[2]; tl[kk * 65 + nn + 3] = v[3]; } } }
; DI void phase_weights_a(LAS unsigned char* lds, PP p, int l, int bid, int nblk) {
;     ...
;     transpose_job<0>(lds, p->in[19] + (size_t)l * 1024 * 2048, 1024, 2048, (bf16_t*)(ws + O_WUPS), bid, nblk);
.LBB0_336:
	s_ashr_i32 s2, s26, 31
	s_lshr_b32 s2, s2, 27
	s_add_i32 s27, s26, s2
	s_and_b32 s2, s27, 0x3ffffe0
	s_sub_i32 s2, s26, s2
	s_lshl_b32 s2, s2, 6
	v_or_b32_e32 v2, s2, v14
	s_movk_i32 s3, 0x800
	v_cmp_gt_i32_e32 vcc, s3, v2
	v_mov_b32_e32 v4, 0
	v_mov_b32_e32 v5, 0
	v_mov_b32_e32 v6, 0
	v_mov_b32_e32 v7, 0
	v_mov_b32_e32 v8, 0
	v_mov_b32_e32 v9, 0
	v_mov_b32_e32 v10, 0
	v_mov_b32_e32 v11, 0
	s_and_saveexec_b64 s[20:21], vcc
	s_cbranch_execz .LBB0_338
	s_ashr_i32 s3, s2, 31
	v_lshl_add_u64 v[4:5], s[2:3], 2, v[0:1]
	s_lshl_b32 s3, s27, 1
	s_andn2_b32 s3, s3, 63
	v_add_u32_e32 v6, s3, v13
	v_add_u32_e32 v8, s3, v17
	v_ashrrev_i32_e32 v7, 31, v6
	v_ashrrev_i32_e32 v9, 31, v8
	v_lshlrev_b64 v[6:7], 13, v[6:7]
	v_lshlrev_b64 v[8:9], 13, v[8:9]
	v_lshl_add_u64 v[6:7], v[4:5], 0, v[6:7]
	v_lshl_add_u64 v[4:5], v[4:5], 0, v[8:9]
	global_load_dwordx4 v[8:11], v[6:7], off nt
	s_nop 0
	global_load_dwordx4 v[4:7], v[4:5], off nt
.LBB0_338:
	s_or_b64 exec, exec, s[20:21]
	s_add_i32 s28, s85, s26
	s_addk_i32 s28, 0xffa0
	v_add_u32_e32 v2, 0x2080, v19
	s_cmpk_lt_i32 s28, 0x200
	s_waitcnt vmcnt(1)
	ds_write2_b32 v19, v8, v9 offset1:1
	ds_write2_b32 v19, v10, v11 offset0:2 offset1:3
	s_waitcnt vmcnt(0)
	ds_write2_b32 v2, v4, v5 offset1:1
	v_add_u32_e32 v2, 0x2088, v19
	s_cselect_b64 s[20:21], -1, 0
	s_cmpk_gt_i32 s28, 0x1ff
	ds_write2_b32 v2, v6, v7 offset1:1
	s_cbranch_scc1 .LBB0_342
	s_ashr_i32 s3, s28, 31
	s_lshr_b32 s3, s3, 27
	s_add_i32 s3, s28, s3
	s_and_b32 s22, s3, 0x3ffffe0
	s_sub_i32 s22, s28, s22
	s_lshl_b32 s24, s22, 6
	v_or_b32_e32 v2, s24, v14
	s_movk_i32 s22, 0x800
	v_cmp_gt_i32_e32 vcc, s22, v2
	v_mov_b32_e32 v4, 0
	v_mov_b32_e32 v5, 0
	v_mov_b32_e32 v6, 0
	v_mov_b32_e32 v7, 0
	v_mov_b32_e32 v8, 0
	v_mov_b32_e32 v9, 0
	v_mov_b32_e32 v10, 0
	v_mov_b32_e32 v11, 0
	s_and_saveexec_b64 s[22:23], vcc
	s_cbranch_execz .LBB0_341
	s_lshl_b32 s3, s3, 1
	s_andn2_b32 s3, s3, 63
	v_add_u32_e32 v6, s3, v13
	v_add_u32_e32 v8, s3, v17
	s_ashr_i32 s25, s24, 31
	v_ashrrev_i32_e32 v7, 31, v6
	v_ashrrev_i32_e32 v9, 31, v8
	v_lshl_add_u64 v[4:5], s[24:25], 2, v[0:1]
	v_lshlrev_b64 v[6:7], 13, v[6:7]
	v_lshlrev_b64 v[8:9], 13, v[8:9]
	v_lshl_add_u64 v[6:7], v[4:5], 0, v[6:7]
	v_lshl_add_u64 v[4:5], v[4:5], 0, v[8:9]
	global_load_dwordx4 v[8:11], v[6:7], off nt
	s_nop 0
	global_load_dwordx4 v[4:7], v[4:5], off nt

; #define LAS __attribute__((address_space(3)))
; template <int MODE> DI void transpose_job(LAS unsigned char* lds, const float* src, int K, int N, bf16_t* dst, int bid, int nblk) {
;     ...
;     for (int t0 = bid; t0 < ntile; t0 += 2 * nblk) {
; #pragma unroll
;         for (int q = 0; q < 2; ++q) { const int t = t0 + q * nblk; LAS float* tl = (LAS float*)(lds + q * 16640);
;             if (t < ntile) { const int k0 = (t / tn) * 64, n0 = (t % tn) * 64;
; #pragma unroll
;                 for (int i = 0; i < 2; ++i) { const int kk = (tid >> 4) + 32 * i, nn = (tid & 15) * 4;
;                     f32x4 v = {0.f, 0.f, 0.f, 0.f}; if (n0 + nn < N) v = *(const f32x4*)(src + (size_t)(k0 + kk) * N + n0 + nn);
;                     tl[kk * 65 + nn] = v[0]; tl[kk * 65 + nn + 1] = v[1]; tl[kk * 65 + nn + 2] = v[2]; tl[kk * 65 + nn + 3] = v[3]; } } }
; DI void phase_weights_a(LAS unsigned char* lds, PP p, int l, int bid, int nblk) {
;     ...
;     transpose_job<1>(lds, p->in[4] + (size_t)l * 2048 * 9232, 2048, 9232, (bf16_t*)(ws + O_WIN), bid, nblk);
.LBB0_1331:
	s_mul_hi_i32 s2, s20, 0xe1fc780f
	s_add_i32 s2, s2, s20
	s_lshr_b32 s3, s2, 31
	s_ashr_i32 s25, s2, 7
	s_add_i32 s25, s25, s3
	s_mul_i32 s2, s25, 0x91
	s_sub_i32 s2, s20, s2
	s_lshl_b32 s4, s2, 6
	v_or_b32_e32 v2, s4, v16
	v_cmp_gt_i32_e32 vcc, s34, v2
	v_mov_b32_e32 v4, 0
	v_mov_b32_e32 v5, 0
	v_mov_b32_e32 v6, 0
	v_mov_b32_e32 v7, 0
	v_mov_b32_e32 v8, 0
	v_mov_b32_e32 v9, 0
	v_mov_b32_e32 v10, 0
	v_mov_b32_e32 v11, 0
	s_and_saveexec_b64 s[2:3], vcc
	s_cbranch_execz .LBB0_1333
	s_ashr_i32 s5, s4, 31
	v_lshl_add_u64 v[4:5], s[4:5], 2, v[0:1]
	s_lshl_b32 s5, s25, 6
	v_add_u32_e32 v2, s5, v13
	v_mad_i64_i32 v[6:7], s[22:23], v2, s35, v[4:5]
	v_add_u32_e32 v2, s5, v19
	v_mad_i64_i32 v[4:5], s[22:23], v2, s35, v[4:5]
	global_load_dwordx4 v[8:11], v[6:7], off nt
	s_nop 0
	global_load_dwordx4 v[4:7], v[4:5], off nt
.LBB0_1333:
	s_or_b64 exec, exec, s[2:3]
	s_add_i32 s24, s20, s86
	v_add_u32_e32 v2, 0x2080, v21
	s_cmpk_lt_i32 s24, 0x1220
	s_waitcnt vmcnt(1)
	ds_write2_b32 v21, v8, v9 offset1:1
	ds_write2_b32 v21, v10, v11 offset0:2 offset1:3
	s_waitcnt vmcnt(0)
	ds_write2_b32 v2, v4, v5 offset1:1
	v_add_u32_e32 v2, 0x2088, v21
	s_cselect_b64 s[2:3], -1, 0
	s_cmpk_gt_i32 s24, 0x121f
	s_mul_hi_i32 s26, s24, 0xe1fc780f
	ds_write2_b32 v2, v6, v7 offset1:1
	s_cbranch_scc1 .LBB0_1337
	s_add_i32 s5, s26, s24
	s_lshr_b32 s20, s5, 31
	s_ashr_i32 s5, s5, 7
	s_add_i32 s5, s5, s20
	s_mul_i32 s20, s5, 0x91
	s_sub_i32 s20, s24, s20
	s_lshl_b32 s22, s20, 6
	v_or_b32_e32 v2, s22, v16
	v_cmp_gt_i32_e32 vcc, s34, v2
	v_mov_b32_e32 v4, 0
	v_mov_b32_e32 v5, 0
	v_mov_b32_e32 v6, 0
	v_mov_b32_e32 v7, 0
	v_mov_b32_e32 v8, 0
	v_mov_b32_e32 v9, 0
	v_mov_b32_e32 v10, 0
	v_mov_b32_e32 v11, 0
	s_and_saveexec_b64 s[20:21], vcc
	s_cbranch_execz .LBB0_1336
	s_ashr_i32 s23, s22, 31
	s_lshl_b32 s5, s5, 6
	v_lshl_add_u64 v[4:5], s[22:23], 2, v[0:1]
	v_add_u32_e32 v2, s5, v13
	v_mad_i64_i32 v[6:7], s[22:23], v2, s35, v[4:5]
	v_add_u32_e32 v2, s5, v19
	v_mad_i64_i32 v[4:5], s[22:23], v2, s35, v[4:5]
	global_load_dwordx4 v[8:11], v[6:7], off nt
	s_nop 0
	global_load_dwordx4 v[4:7], v[4:5], off nt

; #define LAS __attribute__((address_space(3)))
; template <int MODE> DI void transpose_job(LAS unsigned char* lds, const float* src, int K, int N, bf16_t* dst, int bid, int nblk) {
;     ...
;     for (int t0 = bid; t0 < ntile; t0 += 2 * nblk) {
; #pragma unroll
;         for (int q = 0; q < 2; ++q) { const int t = t0 + q * nblk; LAS float* tl = (LAS float*)(lds + q * 16640);
;             if (t < ntile) { const int k0 = (t / tn) * 64, n0 = (t % tn) * 64;
; #pragma unroll
;                 for (int i = 0; i < 2; ++i) { const int kk = (tid >> 4) + 32 * i, nn = (tid & 15) * 4;
;                     f32x4 v = {0.f, 0.f, 0.f, 0.f}; if (n0 + nn < N) v = *(const f32x4*)(src + (size_t)(k0 + kk) * N + n0 + nn);
;                     tl[kk * 65 + nn] = v[0]; tl[kk * 65 + nn + 1] = v[1]; tl[kk * 65 + nn + 2] = v[2]; tl[kk * 65 + nn + 3] = v[3]; } } }
; DI void phase_weights_a(LAS unsigned char* lds, PP p, int l, int bid, int nblk) {
;     ...
;     transpose_job<0>(lds, p->in[13] + (size_t)l * 1024 * 1024, 1024, 1024, (bf16_t*)(ws + O_WGLU), bid, nblk);
.LBB0_1356:
	s_ashr_i32 s4, s22, 31
	s_lshr_b32 s4, s4, 28
	s_add_i32 s27, s22, s4
	s_and_b32 s4, s27, 0x3fffff0
	s_sub_i32 s4, s22, s4
	s_lshl_b32 s4, s4, 6
	v_or_b32_e32 v2, s4, v14
	v_cmp_gt_i32_e32 vcc, s30, v2
	v_mov_b32_e32 v4, 0
	v_mov_b32_e32 v5, 0
	v_mov_b32_e32 v6, 0
	v_mov_b32_e32 v7, 0
	v_mov_b32_e32 v8, 0
	v_mov_b32_e32 v9, 0
	v_mov_b32_e32 v10, 0
	v_mov_b32_e32 v11, 0
	s_and_saveexec_b64 s[20:21], vcc
	s_cbranch_execz .LBB0_1358
	s_ashr_i32 s5, s4, 31
	v_lshl_add_u64 v[4:5], s[4:5], 2, v[0:1]
	s_lshl_b32 s5, s27, 2
	s_andn2_b32 s5, s5, 63
	v_add_u32_e32 v6, s5, v13
	v_add_u32_e32 v8, s5, v17
	v_ashrrev_i32_e32 v7, 31, v6
	v_ashrrev_i32_e32 v9, 31, v8
	v_lshlrev_b64 v[6:7], 12, v[6:7]
	v_lshlrev_b64 v[8:9], 12, v[8:9]
	v_lshl_add_u64 v[6:7], v[4:5], 0, v[6:7]
	v_lshl_add_u64 v[4:5], v[4:5], 0, v[8:9]
	global_load_dwordx4 v[8:11], v[6:7], off nt
	s_nop 0
	global_load_dwordx4 v[4:7], v[4:5], off nt
.LBB0_1358:
	s_or_b64 exec, exec, s[20:21]
	s_add_i32 s26, s22, s86
	v_add_u32_e32 v2, 0x2080, v19
	s_cmpk_lt_i32 s26, 0x100
	s_waitcnt vmcnt(1)
	ds_write2_b32 v19, v8, v9 offset1:1
	ds_write2_b32 v19, v10, v11 offset0:2 offset1:3
	s_waitcnt vmcnt(0)
	ds_write2_b32 v2, v4, v5 offset1:1
	v_add_u32_e32 v2, 0x2088, v19
	s_cselect_b64 s[20:21], -1, 0
	s_cmpk_gt_i32 s26, 0xff
	ds_write2_b32 v2, v6, v7 offset1:1
	s_cbranch_scc1 .LBB0_1362
	s_ashr_i32 s5, s26, 31
	s_lshr_b32 s5, s5, 28
	s_add_i32 s5, s26, s5
	s_and_b32 s22, s5, 0x3fffff0
	s_sub_i32 s22, s26, s22
	s_lshl_b32 s24, s22, 6
	v_or_b32_e32 v2, s24, v14
	v_cmp_gt_i32_e32 vcc, s30, v2
	v_mov_b32_e32 v4, 0
	v_mov_b32_e32 v5, 0
	v_mov_b32_e32 v6, 0
	v_mov_b32_e32 v7, 0
	v_mov_b32_e32 v8, 0
	v_mov_b32_e32 v9, 0
	v_mov_b32_e32 v10, 0
	v_mov_b32_e32 v11, 0
	s_and_saveexec_b64 s[22:23], vcc
	s_cbranch_execz .LBB0_1361
	s_lshl_b32 s5, s5, 2
	s_andn2_b32 s5, s5, 63
	v_add_u32_e32 v6, s5, v13
	v_add_u32_e32 v8, s5, v17
	s_ashr_i32 s25, s24, 31
	v_ashrrev_i32_e32 v7, 31, v6
	v_ashrrev_i32_e32 v9, 31, v8
	v_lshl_add_u64 v[4:5], s[24:25], 2, v[0:1]
	v_lshlrev_b64 v[6:7], 12, v[6:7]
	v_lshlrev_b64 v[8:9], 12, v[8:9]
	v_lshl_add_u64 v[6:7], v[4:5], 0, v[6:7]
	v_lshl_add_u64 v[4:5], v[4:5], 0, v[8:9]
	global_load_dwordx4 v[8:11], v[6:7], off nt
	s_nop 0
	global_load_dwordx4 v[4:7], v[4:5], off nt

; #define LAS __attribute__((address_space(3)))
; template <int MODE> DI void transpose_job(LAS unsigned char* lds, const float* src, int K, int N, bf16_t* dst, int bid, int nblk) {
;     ...
;     for (int t0 = bid; t0 < ntile; t0 += 2 * nblk) {
; #pragma unroll
;         for (int q = 0; q < 2; ++q) { const int t = t0 + q * nblk; LAS float* tl = (LAS float*)(lds + q * 16640);
;             if (t < ntile) { const int k0 = (t / tn) * 64, n0 = (t % tn) * 64;
; #pragma unroll
;                 for (int i = 0; i < 2; ++i) { const int kk = (tid >> 4) + 32 * i, nn = (tid & 15) * 4;
;                     f32x4 v = {0.f, 0.f, 0.f, 0.f}; if (n0 + nn < N) v = *(const f32x4*)(src + (size_t)(k0 + kk) * N + n0 + nn);
;                     tl[kk * 65 + nn] = v[0]; tl[kk * 65 + nn + 1] = v[1]; tl[kk * 65 + nn + 2] = v[2]; tl[kk * 65 + nn + 3] = v[3]; } } }
; DI void phase_weights_a(LAS unsigned char* lds, PP p, int l, int bid, int nblk) {
;     ...
;     transpose_job<0>(lds, p->in[19] + (size_t)l * 1024 * 2048, 1024, 2048, (bf16_t*)(ws + O_WUPS), bid, nblk);
.LBB0_1371:
	s_ashr_i32 s2, s20, 31
	s_lshr_b32 s2, s2, 27
	s_add_i32 s25, s20, s2
	s_and_b32 s2, s25, 0x3ffffe0
	s_sub_i32 s2, s20, s2
	s_lshl_b32 s2, s2, 6
	v_or_b32_e32 v2, s2, v14
	v_cmp_gt_i32_e32 vcc, s31, v2
	v_mov_b32_e32 v4, 0
	v_mov_b32_e32 v5, 0
	v_mov_b32_e32 v6, 0
	v_mov_b32_e32 v7, 0
	v_mov_b32_e32 v8, 0
	v_mov_b32_e32 v9, 0
	v_mov_b32_e32 v10, 0
	v_mov_b32_e32 v11, 0
	s_and_saveexec_b64 s[4:5], vcc
	s_cbranch_execz .LBB0_1373
	s_ashr_i32 s3, s2, 31
	v_lshl_add_u64 v[4:5], s[2:3], 2, v[0:1]
	s_lshl_b32 s3, s25, 1
	s_andn2_b32 s3, s3, 63
	v_add_u32_e32 v6, s3, v13
	v_add_u32_e32 v8, s3, v17
	v_ashrrev_i32_e32 v7, 31, v6
	v_ashrrev_i32_e32 v9, 31, v8
	v_lshlrev_b64 v[6:7], 13, v[6:7]
	v_lshlrev_b64 v[8:9], 13, v[8:9]
	v_lshl_add_u64 v[6:7], v[4:5], 0, v[6:7]
	v_lshl_add_u64 v[4:5], v[4:5], 0, v[8:9]
	global_load_dwordx4 v[8:11], v[6:7], off nt
	s_nop 0
	global_load_dwordx4 v[4:7], v[4:5], off nt
.LBB0_1373:
	s_or_b64 exec, exec, s[4:5]
	s_add_i32 s24, s20, s86
	v_add_u32_e32 v2, 0x2080, v19
	s_cmpk_lt_i32 s24, 0x200
	s_waitcnt vmcnt(1)
	ds_write2_b32 v19, v8, v9 offset1:1
	ds_write2_b32 v19, v10, v11 offset0:2 offset1:3
	s_waitcnt vmcnt(0)
	ds_write2_b32 v2, v4, v5 offset1:1
	v_add_u32_e32 v2, 0x2088, v19
	s_cselect_b64 s[4:5], -1, 0
	s_cmpk_gt_i32 s24, 0x1ff
	ds_write2_b32 v2, v6, v7 offset1:1
	s_cbranch_scc1 .LBB0_1377
	s_ashr_i32 s3, s24, 31
	s_lshr_b32 s3, s3, 27
	s_add_i32 s3, s24, s3
	s_and_b32 s20, s3, 0x3ffffe0
	s_sub_i32 s20, s24, s20
	s_lshl_b32 s22, s20, 6
	v_or_b32_e32 v2, s22, v14
	v_cmp_gt_i32_e32 vcc, s31, v2
	v_mov_b32_e32 v4, 0
	v_mov_b32_e32 v5, 0
	v_mov_b32_e32 v6, 0
	v_mov_b32_e32 v7, 0
	v_mov_b32_e32 v8, 0
	v_mov_b32_e32 v9, 0
	v_mov_b32_e32 v10, 0
	v_mov_b32_e32 v11, 0
	s_and_saveexec_b64 s[20:21], vcc
	s_cbranch_execz .LBB0_1376
	s_lshl_b32 s3, s3, 1
	s_andn2_b32 s3, s3, 63
	v_add_u32_e32 v6, s3, v13
	v_add_u32_e32 v8, s3, v17
	s_ashr_i32 s23, s22, 31
	v_ashrrev_i32_e32 v7, 31, v6
	v_ashrrev_i32_e32 v9, 31, v8
	v_lshl_add_u64 v[4:5], s[22:23], 2, v[0:1]
	v_lshlrev_b64 v[6:7], 13, v[6:7]
	v_lshlrev_b64 v[8:9], 13, v[8:9]
	v_lshl_add_u64 v[6:7], v[4:5], 0, v[6:7]
	v_lshl_add_u64 v[4:5], v[4:5], 0, v[8:9]
	global_load_dwordx4 v[8:11], v[6:7], off nt
	s_nop 0
	global_load_dwordx4 v[4:7], v[4:5], off nt
